# conv in-projection u-tile epilogue: u stores coalesced (4 lanes per 64 contiguous bytes) through a per-wave LDS transpose
# speedup vs baseline: 1.0355x; 1.0044x over previous
; __device__ __forceinline__ unsigned cvt_pk_bf16(float lo, float hi) { f32x2_t v = {lo, hi}; bf16x2_t b = __builtin_convertvector(v, bf16x2_t); return __builtin_bit_cast(unsigned, b); }
;     __device__ __forceinline__ void operator()(const f32x4 (&acc)[2][2][4][2], const Unit& u, int wr, int wc, int fr, int fq) const {
;     ...
;         if (u.pn < 8) {
;             const int col0 = (2 * (u.pn & 3) + (u.pn >> 2)) * 128 + wc * 32 + 8 * fq;
; #pragma unroll
;             for (int ai = 0; ai < 2; ++ai)
; #pragma unroll
;                 for (int m = 0; m < 4; ++m) { const int row = row0 + ai * HALF + m * 16; const float r = rr[ai][m], r2 = r * r;
;                     const f32x4 v0 = acc[ai][0][m][0] * acc[ai][1][m][0] * r2, v1 = acc[ai][0][m][1] * acc[ai][1][m][1] * r2;
;                     u32x4 w; w.x = cvt_pk_bf16(v0[0], v0[1]); w.y = cvt_pk_bf16(v0[2], v0[3]); w.z = cvt_pk_bf16(v1[0], v1[1]); w.w = cvt_pk_bf16(v1[2], v1[3]);
;                     *(u32x4*)(U + (size_t)row * 1024 + col0) = w; }
;             asm volatile("s_waitcnt vmcnt(0)" ::: "memory");
.LBB0_421:
	s_and_b64 vcc, exec, s[6:7]
	s_cbranch_vccz .LBB0_423
	s_lshl_b32 s3, s37, 1
	s_and_b32 s3, s3, 6
	s_lshr_b32 s6, s37, 2
	s_add_i32 s3, s3, s6
	v_lshl_or_b32 v130, s3, 7, v250
	v_mul_f32_e32 v132, v198, v198
	v_pk_mul_f32 v[124:125], v[128:129], v[124:125]
	v_pk_mul_f32 v[122:123], v[126:127], v[122:123]
	v_pk_mul_f32 v[116:117], v[116:117], v[120:121]
	v_pk_mul_f32 v[114:115], v[114:115], v[118:119]
	v_ashrrev_i32_e32 v131, 31, v130
	v_pk_mul_f32 v[124:125], v[124:125], v[132:133] op_sel_hi:[1,0]
	v_pk_mul_f32 v[122:123], v[122:123], v[132:133] op_sel_hi:[1,0]
	v_pk_mul_f32 v[118:119], v[116:117], v[132:133] op_sel_hi:[1,0]
	v_pk_mul_f32 v[116:117], v[114:115], v[132:133] op_sel_hi:[1,0]
	v_cvt_pk_bf16_f32 v114, v122, v123
	v_cvt_pk_bf16_f32 v115, v124, v125
	v_cvt_pk_bf16_f32 v116, v116, v117
	v_cvt_pk_bf16_f32 v117, v118, v119
	v_lshl_add_u64 v[118:119], v[130:131], 1, v[200:201]
	v_readfirstlane_b32 s7, v0
	v_and_b32_e32 v138, 15, v242
	v_lshrrev_b32_e32 v139, 4, v242
	v_lshrrev_b32_e32 v136, 2, v138
	v_xor_b32_e32 v136, v136, v139
	v_lshlrev_b32_e32 v136, 4, v136
	v_lshl_or_b32 v136, v138, 6, v136
	v_lshrrev_b32_e32 v140, 2, v242
	v_and_b32_e32 v141, 3, v242
	v_lshrrev_b32_e32 v137, 2, v140
	v_xor_b32_e32 v137, v137, v141
	v_lshlrev_b32_e32 v137, 4, v137
	v_lshl_or_b32 v137, v140, 6, v137
	v_sub_u32_e32 v140, v140, v138
	v_sub_u32_e32 v141, v141, v139
	v_lshlrev_b32_e32 v140, 11, v140
	v_lshl_add_u32 v140, v141, 4, v140
	v_ashrrev_i32_e32 v141, 31, v140
	s_lshr_b32 s7, s7, 6
	s_lshl_b32 s7, s7, 10
	s_add_i32 s7, s7, 0x23000
	v_add_u32_e32 v136, s7, v136
	v_add_u32_e32 v137, s7, v137
	v_lshl_add_u64 v[118:119], v[118:119], 0, v[140:141]
	ds_write_b128 v136, v[114:117]
	ds_read_b128 v[142:145], v137
	v_mov_b32_e32 v150, v118
	v_mov_b32_e32 v151, v119
	v_pk_mul_f32 v[100:101], v[100:101], v[104:105]
	v_pk_mul_f32 v[98:99], v[98:99], v[102:103]
	v_mul_f32_e32 v114, v196, v196
	v_pk_mul_f32 v[108:109], v[108:109], v[112:113]
	v_pk_mul_f32 v[106:107], v[106:107], v[110:111]
	v_pk_mul_f32 v[102:103], v[100:101], v[114:115] op_sel_hi:[1,0]
	v_pk_mul_f32 v[100:101], v[98:99], v[114:115] op_sel_hi:[1,0]
	s_mov_b32 s3, 0x8000
	v_pk_mul_f32 v[108:109], v[108:109], v[114:115] op_sel_hi:[1,0]
	v_pk_mul_f32 v[106:107], v[106:107], v[114:115] op_sel_hi:[1,0]
	v_cvt_pk_bf16_f32 v100, v100, v101
	v_cvt_pk_bf16_f32 v101, v102, v103
	v_add_co_u32_e32 v102, vcc, s3, v118
	v_cvt_pk_bf16_f32 v98, v106, v107
	v_cvt_pk_bf16_f32 v99, v108, v109
	v_addc_co_u32_e32 v103, vcc, 0, v119, vcc
	s_waitcnt lgkmcnt(0)
	global_store_dwordx4 v[150:151], v[142:145], off
	ds_write_b128 v136, v[98:101]
	ds_read_b128 v[146:149], v137
	v_mov_b32_e32 v152, v102
	v_mov_b32_e32 v153, v103
	v_pk_mul_f32 v[84:85], v[84:85], v[88:89]
	v_pk_mul_f32 v[82:83], v[82:83], v[86:87]
	v_mul_f32_e32 v98, v192, v192
	v_pk_mul_f32 v[92:93], v[92:93], v[96:97]
	v_pk_mul_f32 v[90:91], v[90:91], v[94:95]
	v_pk_mul_f32 v[86:87], v[84:85], v[98:99] op_sel_hi:[1,0]
	v_pk_mul_f32 v[84:85], v[82:83], v[98:99] op_sel_hi:[1,0]
	s_mov_b32 s3, 0x10000
	v_pk_mul_f32 v[92:93], v[92:93], v[98:99] op_sel_hi:[1,0]
	v_pk_mul_f32 v[90:91], v[90:91], v[98:99] op_sel_hi:[1,0]
	v_cvt_pk_bf16_f32 v84, v84, v85
	v_cvt_pk_bf16_f32 v85, v86, v87
	v_add_co_u32_e32 v86, vcc, s3, v118
	v_cvt_pk_bf16_f32 v82, v90, v91
	v_cvt_pk_bf16_f32 v83, v92, v93
	v_addc_co_u32_e32 v87, vcc, 0, v119, vcc
	s_waitcnt lgkmcnt(0)
	global_store_dwordx4 v[152:153], v[146:149], off
	ds_write_b128 v136, v[82:85]
	ds_read_b128 v[142:145], v137
	v_mov_b32_e32 v150, v86
	v_mov_b32_e32 v151, v87
	v_pk_mul_f32 v[68:69], v[68:69], v[72:73]
	v_pk_mul_f32 v[66:67], v[66:67], v[70:71]
	v_mul_f32_e32 v82, v194, v194
	v_pk_mul_f32 v[76:77], v[76:77], v[80:81]
	v_pk_mul_f32 v[74:75], v[74:75], v[78:79]
	v_pk_mul_f32 v[70:71], v[68:69], v[82:83] op_sel_hi:[1,0]
	v_pk_mul_f32 v[68:69], v[66:67], v[82:83] op_sel_hi:[1,0]
	s_mov_b32 s3, 0x18000
	v_pk_mul_f32 v[76:77], v[76:77], v[82:83] op_sel_hi:[1,0]
	v_pk_mul_f32 v[74:75], v[74:75], v[82:83] op_sel_hi:[1,0]
	v_cvt_pk_bf16_f32 v68, v68, v69
	v_cvt_pk_bf16_f32 v69, v70, v71
	v_add_co_u32_e32 v70, vcc, s3, v118
	v_cvt_pk_bf16_f32 v66, v74, v75
	v_cvt_pk_bf16_f32 v67, v76, v77
	v_addc_co_u32_e32 v71, vcc, 0, v119, vcc
	s_waitcnt lgkmcnt(0)
; __device__ __forceinline__ unsigned cvt_pk_bf16(float lo, float hi) { f32x2_t v = {lo, hi}; bf16x2_t b = __builtin_convertvector(v, bf16x2_t); return __builtin_bit_cast(unsigned, b); }
;     __device__ __forceinline__ void operator()(const f32x4 (&acc)[2][2][4][2], const Unit& u, int wr, int wc, int fr, int fq) const {
;     ...
; #pragma unroll
;             for (int ai = 0; ai < 2; ++ai)
; #pragma unroll
;                 for (int m = 0; m < 4; ++m) { const int row = row0 + ai * HALF + m * 16; const float r = rr[ai][m], r2 = r * r;
;                     const f32x4 v0 = acc[ai][0][m][0] * acc[ai][1][m][0] * r2, v1 = acc[ai][0][m][1] * acc[ai][1][m][1] * r2;
;                     u32x4 w; w.x = cvt_pk_bf16(v0[0], v0[1]); w.y = cvt_pk_bf16(v0[2], v0[3]); w.z = cvt_pk_bf16(v1[0], v1[1]); w.w = cvt_pk_bf16(v1[2], v1[3]);
;                     *(u32x4*)(U + (size_t)row * 1024 + col0) = w; }
;             asm volatile("s_waitcnt vmcnt(0)" ::: "memory");
	global_store_dwordx4 v[150:151], v[142:145], off
	ds_write_b128 v136, v[66:69]
	ds_read_b128 v[146:149], v137
	v_mov_b32_e32 v152, v70
	v_mov_b32_e32 v153, v71
	v_pk_mul_f32 v[52:53], v[52:53], v[56:57]
	v_pk_mul_f32 v[50:51], v[50:51], v[54:55]
	v_mul_f32_e32 v66, v190, v190
	v_pk_mul_f32 v[60:61], v[60:61], v[64:65]
	v_pk_mul_f32 v[58:59], v[58:59], v[62:63]
	v_pk_mul_f32 v[54:55], v[52:53], v[66:67] op_sel_hi:[1,0]
	v_pk_mul_f32 v[52:53], v[50:51], v[66:67] op_sel_hi:[1,0]
	s_mov_b32 s3, 0x40000
	v_pk_mul_f32 v[60:61], v[60:61], v[66:67] op_sel_hi:[1,0]
	v_pk_mul_f32 v[58:59], v[58:59], v[66:67] op_sel_hi:[1,0]
	v_cvt_pk_bf16_f32 v52, v52, v53
	v_cvt_pk_bf16_f32 v53, v54, v55
	v_add_co_u32_e32 v54, vcc, s3, v118
	v_cvt_pk_bf16_f32 v50, v58, v59
	v_cvt_pk_bf16_f32 v51, v60, v61
	v_addc_co_u32_e32 v55, vcc, 0, v119, vcc
	s_waitcnt lgkmcnt(0)
	global_store_dwordx4 v[152:153], v[146:149], off
	ds_write_b128 v136, v[50:53]
	ds_read_b128 v[142:145], v137
	v_mov_b32_e32 v150, v54
	v_mov_b32_e32 v151, v55
	v_pk_mul_f32 v[36:37], v[36:37], v[40:41]
	v_pk_mul_f32 v[34:35], v[34:35], v[38:39]
	v_mul_f32_e32 v50, v188, v188
	v_pk_mul_f32 v[44:45], v[44:45], v[48:49]
	v_pk_mul_f32 v[42:43], v[42:43], v[46:47]
	v_pk_mul_f32 v[38:39], v[36:37], v[50:51] op_sel_hi:[1,0]
	v_pk_mul_f32 v[36:37], v[34:35], v[50:51] op_sel_hi:[1,0]
	s_mov_b32 s3, 0x48000
	v_pk_mul_f32 v[44:45], v[44:45], v[50:51] op_sel_hi:[1,0]
	v_pk_mul_f32 v[42:43], v[42:43], v[50:51] op_sel_hi:[1,0]
	v_cvt_pk_bf16_f32 v36, v36, v37
	v_cvt_pk_bf16_f32 v37, v38, v39
	v_add_co_u32_e32 v38, vcc, s3, v118
	v_cvt_pk_bf16_f32 v34, v42, v43
	v_cvt_pk_bf16_f32 v35, v44, v45
	v_addc_co_u32_e32 v39, vcc, 0, v119, vcc
	s_waitcnt lgkmcnt(0)
	global_store_dwordx4 v[150:151], v[142:145], off
	ds_write_b128 v136, v[34:37]
	ds_read_b128 v[146:149], v137
	v_mov_b32_e32 v152, v38
	v_mov_b32_e32 v153, v39
	v_pk_mul_f32 v[20:21], v[20:21], v[24:25]
	v_pk_mul_f32 v[18:19], v[18:19], v[22:23]
	v_mul_f32_e32 v34, v186, v186
	v_pk_mul_f32 v[28:29], v[28:29], v[32:33]
	v_pk_mul_f32 v[26:27], v[26:27], v[30:31]
	v_pk_mul_f32 v[22:23], v[20:21], v[34:35] op_sel_hi:[1,0]
	v_pk_mul_f32 v[20:21], v[18:19], v[34:35] op_sel_hi:[1,0]
	s_mov_b32 s3, 0x50000
	v_pk_mul_f32 v[28:29], v[28:29], v[34:35] op_sel_hi:[1,0]
	v_pk_mul_f32 v[26:27], v[26:27], v[34:35] op_sel_hi:[1,0]
	v_cvt_pk_bf16_f32 v20, v20, v21
	v_cvt_pk_bf16_f32 v21, v22, v23
	v_add_co_u32_e32 v22, vcc, s3, v118
	v_cvt_pk_bf16_f32 v18, v26, v27
	v_cvt_pk_bf16_f32 v19, v28, v29
	v_addc_co_u32_e32 v23, vcc, 0, v119, vcc
	s_waitcnt lgkmcnt(0)
	global_store_dwordx4 v[152:153], v[146:149], off
	ds_write_b128 v136, v[18:21]
	ds_read_b128 v[142:145], v137
	v_mov_b32_e32 v150, v22
	v_mov_b32_e32 v151, v23
	v_pk_mul_f32 v[4:5], v[4:5], v[8:9]
	v_pk_mul_f32 v[2:3], v[2:3], v[6:7]
	v_mul_f32_e32 v18, v184, v184
	v_pk_mul_f32 v[12:13], v[12:13], v[16:17]
	v_pk_mul_f32 v[10:11], v[10:11], v[14:15]
	v_pk_mul_f32 v[6:7], v[4:5], v[18:19] op_sel_hi:[1,0]
	v_pk_mul_f32 v[4:5], v[2:3], v[18:19] op_sel_hi:[1,0]
	v_pk_mul_f32 v[12:13], v[12:13], v[18:19] op_sel_hi:[1,0]
	v_pk_mul_f32 v[10:11], v[10:11], v[18:19] op_sel_hi:[1,0]
	v_cvt_pk_bf16_f32 v4, v4, v5
	v_cvt_pk_bf16_f32 v5, v6, v7
	v_add_co_u32_e32 v6, vcc, 0x58000, v118
	v_cvt_pk_bf16_f32 v2, v10, v11
	v_cvt_pk_bf16_f32 v3, v12, v13
	v_addc_co_u32_e32 v7, vcc, 0, v119, vcc
	s_waitcnt lgkmcnt(0)
	global_store_dwordx4 v[150:151], v[142:145], off
	ds_write_b128 v136, v[2:5]
	ds_read_b128 v[146:149], v137
	v_mov_b32_e32 v152, v6
	v_mov_b32_e32 v153, v7
	s_waitcnt vmcnt(0)
	s_waitcnt lgkmcnt(0)
	global_store_dwordx4 v[152:153], v[146:149], off
